# MLA fast128: conflict-free LDS images (K rows 224 B, V^T rows 288 B with key permutation, b128 V reads)
# speedup vs baseline: 1.0054x; 1.0054x over previous
.LBB0_1457:
	s_or_saveexec_b64 s[34:35], s[14:15]
	v_mov_b32_e32 v100, 0
	v_mov_b32_e32 v104, 0
	s_xor_b64 exec, exec, s[34:35]
	s_cbranch_execz .LBB0_1505
	s_and_saveexec_b64 s[6:7], vcc
	s_xor_b64 s[6:7], exec, s[6:7]
	v_lshlrev_b64 v[24:25], 12, v[24:25]
	v_lshl_add_u64 v[24:25], s[82:83], 0, v[24:25]
	v_lshl_add_u64 v[24:25], v[118:119], 1, v[24:25]
	v_lshl_add_u64 v[26:27], v[24:25], 0, s[70:71]
	s_andn2_saveexec_b64 s[6:7], s[6:7]
	v_lshlrev_b64 v[24:25], 10, v[24:25]
	v_lshl_add_u64 v[24:25], v[144:145], 0, v[24:25]
	v_lshl_add_u64 v[26:27], v[118:119], 1, v[24:25]
	s_or_b64 exec, exec, s[6:7]
	global_load_dwordx4 v[24:27], v[26:27], off
	v_or_b32_e32 v30, v52, v209
	v_cmp_gt_i32_e64 s[6:7], 8, v28
	v_cmp_lt_i32_e32 vcc, 7, v28
	v_ashrrev_i32_e32 v31, 31, v30
	s_and_saveexec_b64 s[8:9], vcc
	s_xor_b64 s[8:9], exec, s[8:9]
	v_lshlrev_b64 v[28:29], 12, v[30:31]
	v_lshl_add_u64 v[28:29], s[82:83], 0, v[28:29]
	v_lshl_add_u64 v[28:29], v[120:121], 1, v[28:29]
	v_lshl_add_u64 v[28:29], v[28:29], 0, s[70:71]
	s_andn2_saveexec_b64 s[8:9], s[8:9]
	v_lshlrev_b64 v[28:29], 10, v[30:31]
	v_lshl_add_u64 v[28:29], v[144:145], 0, v[28:29]
	v_lshl_add_u64 v[28:29], v[120:121], 1, v[28:29]
	s_or_b64 exec, exec, s[8:9]
	global_load_dwordx4 v[28:31], v[28:29], off
	v_or_b32_e32 v34, v52, v210
	v_cmp_gt_i32_e64 s[8:9], 8, v32
	v_cmp_lt_i32_e32 vcc, 7, v32
	v_ashrrev_i32_e32 v35, 31, v34
	s_and_saveexec_b64 s[10:11], vcc
	s_xor_b64 s[10:11], exec, s[10:11]
	v_lshlrev_b64 v[32:33], 12, v[34:35]
	v_lshl_add_u64 v[32:33], s[82:83], 0, v[32:33]
	v_lshl_add_u64 v[32:33], v[122:123], 1, v[32:33]
	v_lshl_add_u64 v[32:33], v[32:33], 0, s[70:71]
	s_andn2_saveexec_b64 s[10:11], s[10:11]
	v_lshlrev_b64 v[32:33], 10, v[34:35]
	v_lshl_add_u64 v[32:33], v[144:145], 0, v[32:33]
	v_lshl_add_u64 v[32:33], v[122:123], 1, v[32:33]
	s_or_b64 exec, exec, s[10:11]
	global_load_dwordx4 v[32:35], v[32:33], off
	v_or_b32_e32 v38, v52, v149
	v_cmp_gt_i32_e64 s[10:11], 8, v36
	v_cmp_lt_i32_e32 vcc, 7, v36
	v_ashrrev_i32_e32 v39, 31, v38
	s_and_saveexec_b64 s[12:13], vcc
	s_xor_b64 s[12:13], exec, s[12:13]
	v_lshlrev_b64 v[36:37], 12, v[38:39]
	v_lshl_add_u64 v[36:37], s[82:83], 0, v[36:37]
	v_lshl_add_u64 v[36:37], v[44:45], 1, v[36:37]
	v_lshl_add_u64 v[36:37], v[36:37], 0, s[70:71]
	s_andn2_saveexec_b64 s[12:13], s[12:13]
	v_lshlrev_b64 v[36:37], 10, v[38:39]
	v_lshl_add_u64 v[36:37], v[144:145], 0, v[36:37]
	v_lshl_add_u64 v[36:37], v[44:45], 1, v[36:37]
	s_or_b64 exec, exec, s[12:13]
	global_load_dwordx4 v[36:39], v[36:37], off
	v_cmp_gt_i32_e64 s[12:13], 8, v42
	v_cmp_lt_i32_e32 vcc, 7, v42
	v_or_b32_e32 v42, v52, v152
	v_ashrrev_i32_e32 v43, 31, v42
	s_and_saveexec_b64 s[14:15], vcc
	s_xor_b64 s[14:15], exec, s[14:15]
	v_lshlrev_b64 v[40:41], 12, v[42:43]
	v_lshl_add_u64 v[40:41], s[82:83], 0, v[40:41]
	v_lshl_add_u64 v[40:41], v[46:47], 1, v[40:41]
	v_lshl_add_u64 v[40:41], v[40:41], 0, s[70:71]
	s_andn2_saveexec_b64 s[14:15], s[14:15]
	v_lshlrev_b64 v[40:41], 10, v[42:43]
	v_lshl_add_u64 v[40:41], v[144:145], 0, v[40:41]
	v_lshl_add_u64 v[40:41], v[46:47], 1, v[40:41]
	s_or_b64 exec, exec, s[14:15]
	global_load_dwordx4 v[40:43], v[40:41], off
	v_or_b32_e32 v50, v52, v153
	v_cmp_gt_i32_e64 s[14:15], 8, v48
	v_cmp_lt_i32_e32 vcc, 7, v48
	v_ashrrev_i32_e32 v51, 31, v50
	s_and_saveexec_b64 s[16:17], vcc
	s_xor_b64 s[16:17], exec, s[16:17]
	v_lshlrev_b64 v[48:49], 12, v[50:51]
	v_lshl_add_u64 v[48:49], s[82:83], 0, v[48:49]
	v_lshl_add_u64 v[48:49], v[102:103], 1, v[48:49]
	v_lshl_add_u64 v[48:49], v[48:49], 0, s[70:71]
	s_andn2_saveexec_b64 s[16:17], s[16:17]
	v_lshlrev_b64 v[48:49], 10, v[50:51]
	v_lshl_add_u64 v[48:49], v[144:145], 0, v[48:49]
	v_lshl_add_u64 v[48:49], v[102:103], 1, v[48:49]
	s_or_b64 exec, exec, s[16:17]
	v_and_b32_e32 v155, 0x7e, v105
	v_or_b32_e32 v54, v155, v52
	v_or_b32_e32 v52, 1, v54
	v_ashrrev_i32_e32 v55, 31, v54
	v_lshlrev_b32_e32 v68, 4, v53
	v_ashrrev_i32_e32 v53, 31, v52
	v_lshlrev_b64 v[56:57], 10, v[54:55]
	v_lshlrev_b64 v[52:53], 10, v[52:53]
	v_lshl_add_u64 v[56:57], v[144:145], 0, v[56:57]
	v_mov_b32_e32 v69, v129
	v_lshl_add_u64 v[52:53], v[144:145], 0, v[52:53]
	v_lshl_add_u64 v[56:57], v[56:57], 0, v[68:69]
	v_lshl_add_u64 v[64:65], v[52:53], 0, v[68:69]
	global_load_dwordx4 v[48:51], v[48:49], off
	s_nop 0
	global_load_dwordx4 v[52:55], v[56:57], off offset:128
	s_nop 0
	global_load_dwordx4 v[56:59], v[56:57], off offset:192
	s_nop 0
	global_load_dwordx4 v[60:63], v[64:65], off offset:128
	s_nop 0
	global_load_dwordx4 v[64:67], v[64:65], off offset:192
	v_lshrrev_b32_e32 v70, 3, v101
	v_and_b32_e32 v70, 24, v70
	v_mul_u32_u24_e32 v70, 0x120, v70
	v_and_b32_e32 v71, 2, v155
	v_lshlrev_b32_e32 v71, 1, v71
	v_and_b32_e32 v73, 12, v155
	v_lshl_or_b32 v71, v73, 2, v71
	v_and_b32_e32 v73, 0x60, v155
	v_lshl_or_b32 v71, v73, 1, v71
	v_and_b32_e32 v73, 16, v155
	v_lshrrev_b32_e32 v73, 1, v73
	v_or_b32_e32 v71, v71, v73
	v_add3_u32 v159, s33, v70, v71
	v_mul_u32_u24_e32 v70, 0x90, v133
	v_lshlrev_b32_e32 v70, 1, v70
	v_lshlrev_b64 v[44:45], 1, v[44:45]
	v_lshlrev_b32_e32 v128, 2, v126
	v_add_u32_e32 v156, 0x8080, v127
	v_add3_u32 v160, s33, v70, v125
	v_add_u32_e32 v160, v160, v125
	v_or_b32_e32 v70, 32, v133
	v_or_b32_e32 v71, 64, v133
	v_lshl_add_u64 v[126:127], s[82:83], 0, v[44:45]
	v_lshl_add_u64 v[134:135], v[144:145], 0, v[44:45]
	v_lshlrev_b64 v[44:45], 1, v[46:47]
	v_mul_u32_u24_e32 v73, 0xd0, v70
	v_mul_u32_u24_e32 v74, 0xd0, v71
	v_lshlrev_b64 v[70:71], 1, v[118:119]
	v_lshl_add_u64 v[136:137], s[82:83], 0, v[44:45]
	v_lshl_add_u64 v[138:139], v[144:145], 0, v[44:45]
	v_sub_u32_e32 v44, 0x87f, v148
	v_lshl_add_u64 v[112:113], s[82:83], 0, v[70:71]
	v_lshl_add_u64 v[114:115], v[144:145], 0, v[70:71]
	v_lshlrev_b64 v[70:71], 1, v[120:121]
	v_lshrrev_b32_e32 v44, 8, v44
	v_mul_u32_u24_e32 v72, 0xe0, v133
	v_lshl_add_u64 v[118:119], s[82:83], 0, v[70:71]
	v_lshl_add_u64 v[120:121], v[144:145], 0, v[70:71]
	v_lshlrev_b64 v[70:71], 1, v[122:123]
	v_add_u32_e32 v45, 4, v44
	v_readlane_b32 s16, v253, 26
	v_mov_b32_e32 v80, 0
	v_add_u32_e32 v157, 0xffffff80, v124
	v_lshl_add_u32 v158, v102, 1, v106
	v_lshl_add_u64 v[122:123], s[82:83], 0, v[70:71]
	v_lshl_add_u64 v[124:125], v[144:145], 0, v[70:71]
	v_lshl_add_u64 v[140:141], v[102:103], 1, s[82:83]
	v_lshl_add_u64 v[142:143], v[102:103], 1, v[144:145]
	v_and_b32_e32 v163, 28, v45
	v_mov_b32_e32 v45, v44
	v_mov_b32_e32 v46, v44
	v_mov_b32_e32 v47, v44
	v_lshl_add_u64 v[144:145], v[144:145], 0, v[68:69]
	v_add_u32_e32 v164, s16, v105
	v_add_u32_e32 v164, 0xc00, v164
	s_mov_b32 s53, 0
	v_add_u32_e32 v165, v107, v72
	v_subrev_u32_e32 v161, s33, v146
	v_mul_u32_u24_e32 v161, 0x4ec5, v161
	v_lshrrev_b32_e32 v161, 22, v161
	v_lshl_add_u32 v161, v161, 4, v146
	v_subrev_u32_e32 v162, s33, v147
	v_mul_u32_u24_e32 v162, 0x4ec5, v162
	v_lshrrev_b32_e32 v162, 22, v162
	v_lshl_add_u32 v162, v162, 4, v147
	v_subrev_u32_e32 v166, s33, v150
	v_mul_u32_u24_e32 v166, 0x4ec5, v166
	v_lshrrev_b32_e32 v166, 22, v166
	v_lshl_add_u32 v166, v166, 4, v150
	v_subrev_u32_e32 v167, s33, v151
	v_mul_u32_u24_e32 v167, 0x4ec5, v167
	v_lshrrev_b32_e32 v167, 22, v167
	v_lshl_add_u32 v167, v167, 4, v151
	v_subrev_u32_e32 v188, s33, v154
	v_mul_u32_u24_e32 v188, 0x4ec5, v188
	v_lshrrev_b32_e32 v188, 22, v188
	v_lshl_add_u32 v188, v188, 4, v154
	v_subrev_u32_e32 v211, s33, v158
	v_mul_u32_u24_e32 v211, 0x4ec5, v211
	v_lshrrev_b32_e32 v211, 22, v211
	v_lshl_add_u32 v211, v211, 4, v158
	v_mov_b32_e32 v81, v80
	v_mov_b32_e32 v82, v80
	v_mov_b32_e32 v83, v80
	v_mov_b32_e32 v76, v80
	v_mov_b32_e32 v77, v80
	v_mov_b32_e32 v78, v80
	v_mov_b32_e32 v79, v80
	v_mov_b32_e32 v72, v80
	v_mov_b32_e32 v73, v80
	v_mov_b32_e32 v74, v80
	v_mov_b32_e32 v75, v80
	v_mov_b32_e32 v68, v80
	v_mov_b32_e32 v69, v80
	v_mov_b32_e32 v70, v80
	v_mov_b32_e32 v71, v80
	v_mov_b32_e32 v96, v80
	v_mov_b32_e32 v97, v80
	v_mov_b32_e32 v98, v80
	v_mov_b32_e32 v99, v80
	v_mov_b32_e32 v92, v80
	v_mov_b32_e32 v93, v80
	v_mov_b32_e32 v94, v80
	v_mov_b32_e32 v95, v80
	v_mov_b32_e32 v88, v80
	v_mov_b32_e32 v89, v80
	v_mov_b32_e32 v90, v80
	v_mov_b32_e32 v91, v80
	v_mov_b32_e32 v84, v80
	v_mov_b32_e32 v85, v80
	v_mov_b32_e32 v86, v80
	v_mov_b32_e32 v87, v80
	v_mov_b32_e32 v104, v80
	v_mov_b32_e32 v105, v80
	v_mov_b32_e32 v106, v80
	v_mov_b32_e32 v107, v80
	v_mov_b32_e32 v100, v80
	v_mov_b32_e32 v101, v80
	v_mov_b32_e32 v102, v80
	v_mov_b32_e32 v103, v80
	v_readfirstlane_b32 s60, v131
	s_nop 0
	s_cmp_lt_u32 s60, 0x100
	s_cbranch_scc1 .Lmla_stg_pre
	s_barrier

.LBB0_1483:
	s_add_i32 s53, s53, 1
	ds_read_b128 v[212:215], v165
	ds_read_b128 v[216:219], v165 offset:64
	ds_read_b128 v[220:223], v165 offset:128
	ds_read_b128 v[224:227], v165 offset:3584
	ds_read_b128 v[228:231], v165 offset:3648
	s_waitcnt lgkmcnt(4)
	v_mfma_f32_16x16x32_bf16 v[232:235], v[212:215], v[0:3], 0
	v_mfma_f32_16x16x32_bf16 v[240:243], v[212:215], v[12:15], 0
	ds_read_b128 v[212:215], v165 offset:3712
	s_waitcnt lgkmcnt(4)
	v_mfma_f32_16x16x32_bf16 v[232:235], v[216:219], v[4:7], v[232:235]
	v_mfma_f32_16x16x32_bf16 v[240:243], v[216:219], v[16:19], v[240:243]
	ds_read_b128 v[216:219], v165 offset:7168
	s_waitcnt lgkmcnt(4)
	v_mfma_f32_16x16x32_bf16 v[232:235], v[220:223], v[8:11], v[232:235]
	v_mfma_f32_16x16x32_bf16 v[240:243], v[220:223], v[20:23], v[240:243]
	ds_read_b128 v[220:223], v165 offset:7232
	s_waitcnt lgkmcnt(4)
	v_mfma_f32_16x16x32_bf16 v[236:239], v[224:227], v[0:3], 0
	v_mfma_f32_16x16x32_bf16 v[244:247], v[224:227], v[12:15], 0
	ds_read_b128 v[224:227], v165 offset:7296
	s_waitcnt lgkmcnt(4)
	v_mfma_f32_16x16x32_bf16 v[236:239], v[228:231], v[4:7], v[236:239]
	v_mfma_f32_16x16x32_bf16 v[244:247], v[228:231], v[16:19], v[244:247]
	v_exp_f32_e32 v232, v232
	ds_read_b128 v[228:231], v165 offset:10752
	s_waitcnt lgkmcnt(4)
	v_mfma_f32_16x16x32_bf16 v[236:239], v[212:215], v[8:11], v[236:239]
	v_exp_f32_e32 v233, v233
	v_mfma_f32_16x16x32_bf16 v[244:247], v[212:215], v[20:23], v[244:247]
	v_exp_f32_e32 v234, v234
	ds_read_b128 v[212:215], v165 offset:10816
	s_waitcnt lgkmcnt(4)
	v_mfma_f32_16x16x32_bf16 v[168:171], v[216:219], v[0:3], 0
	v_exp_f32_e32 v235, v235
	v_mfma_f32_16x16x32_bf16 v[176:179], v[216:219], v[12:15], 0
	v_cvt_pk_bf16_f32 v232, v232, v233
	v_cvt_pk_bf16_f32 v233, v234, v235
	ds_read_b128 v[216:219], v165 offset:10880
	s_waitcnt lgkmcnt(4)
	v_mfma_f32_16x16x32_bf16 v[168:171], v[220:223], v[4:7], v[168:171]
	v_exp_f32_e32 v240, v240
	v_mfma_f32_16x16x32_bf16 v[176:179], v[220:223], v[16:19], v[176:179]
	v_exp_f32_e32 v241, v241
	ds_read_b128 v[220:223], v160 offset:28672
	s_waitcnt lgkmcnt(4)
	v_mfma_f32_16x16x32_bf16 v[168:171], v[224:227], v[8:11], v[168:171]
	v_exp_f32_e32 v242, v242
	v_mfma_f32_16x16x32_bf16 v[176:179], v[224:227], v[20:23], v[176:179]
	v_exp_f32_e32 v243, v243
	ds_read_b128 v[224:227], v160 offset:33280
	s_waitcnt lgkmcnt(4)
	v_mfma_f32_16x16x32_bf16 v[172:175], v[228:231], v[0:3], 0
	v_cvt_pk_bf16_f32 v240, v240, v241
	v_cvt_pk_bf16_f32 v241, v242, v243
	v_mfma_f32_16x16x32_bf16 v[108:111], v[228:231], v[12:15], 0
	v_exp_f32_e32 v236, v236
	ds_read_b128 v[228:231], v160 offset:37888
	s_waitcnt lgkmcnt(4)
	v_mfma_f32_16x16x32_bf16 v[172:175], v[212:215], v[4:7], v[172:175]
	v_exp_f32_e32 v237, v237
	v_mfma_f32_16x16x32_bf16 v[108:111], v[212:215], v[16:19], v[108:111]
	v_exp_f32_e32 v238, v238
	ds_read_b128 v[212:215], v160 offset:42496
	s_waitcnt lgkmcnt(4)
	v_mfma_f32_16x16x32_bf16 v[172:175], v[216:219], v[8:11], v[172:175]
	v_exp_f32_e32 v239, v239
	v_mfma_f32_16x16x32_bf16 v[108:111], v[216:219], v[20:23], v[108:111]
	v_cvt_pk_bf16_f32 v234, v236, v237
	v_cvt_pk_bf16_f32 v235, v238, v239
	ds_read_b128 v[216:219], v160 offset:47104
	s_waitcnt lgkmcnt(4)
	v_mfma_f32_16x16x32_bf16 v[84:87], v[220:223], v[232:235], v[84:87]
	v_exp_f32_e32 v244, v244
	v_exp_f32_e32 v245, v245
	v_exp_f32_e32 v246, v246
	v_exp_f32_e32 v247, v247
	v_cvt_pk_bf16_f32 v242, v244, v245
	v_cvt_pk_bf16_f32 v243, v246, v247
	v_exp_f32_e32 v168, v168
	v_exp_f32_e32 v169, v169
	v_mfma_f32_16x16x32_bf16 v[68:71], v[220:223], v[240:243], v[68:71]
	v_exp_f32_e32 v170, v170
	ds_read_b128 v[220:223], v165 offset:14336
	s_waitcnt lgkmcnt(4)
	v_mfma_f32_16x16x32_bf16 v[88:91], v[224:227], v[232:235], v[88:91]
	v_exp_f32_e32 v171, v171
	v_mfma_f32_16x16x32_bf16 v[72:75], v[224:227], v[240:243], v[72:75]
	v_cvt_pk_bf16_f32 v168, v168, v169
	v_cvt_pk_bf16_f32 v169, v170, v171
	ds_read_b128 v[224:227], v165 offset:14400
	s_waitcnt lgkmcnt(4)
	v_mfma_f32_16x16x32_bf16 v[92:95], v[228:231], v[232:235], v[92:95]
	v_exp_f32_e32 v176, v176
	v_mfma_f32_16x16x32_bf16 v[76:79], v[228:231], v[240:243], v[76:79]
	v_exp_f32_e32 v177, v177
	ds_read_b128 v[228:231], v165 offset:14464
	s_waitcnt lgkmcnt(4)
	v_mfma_f32_16x16x32_bf16 v[96:99], v[212:215], v[232:235], v[96:99]
	v_exp_f32_e32 v178, v178
	v_mfma_f32_16x16x32_bf16 v[80:83], v[212:215], v[240:243], v[80:83]
	v_exp_f32_e32 v179, v179
	ds_read_b128 v[212:215], v165 offset:17920
	s_waitcnt lgkmcnt(4)
	v_mfma_f32_16x16x32_bf16 v[104:107], v[216:219], v[232:235], v[104:107]
	v_cvt_pk_bf16_f32 v176, v176, v177
	v_cvt_pk_bf16_f32 v177, v178, v179
	v_mfma_f32_16x16x32_bf16 v[100:103], v[216:219], v[240:243], v[100:103]
	v_exp_f32_e32 v172, v172
	ds_read_b128 v[216:219], v165 offset:17984
	s_waitcnt lgkmcnt(4)
	v_mfma_f32_16x16x32_bf16 v[232:235], v[220:223], v[0:3], 0
	v_exp_f32_e32 v173, v173
	v_mfma_f32_16x16x32_bf16 v[240:243], v[220:223], v[12:15], 0
	v_exp_f32_e32 v174, v174
	ds_read_b128 v[220:223], v165 offset:18048
	s_waitcnt lgkmcnt(4)
	v_mfma_f32_16x16x32_bf16 v[232:235], v[224:227], v[4:7], v[232:235]
	v_exp_f32_e32 v175, v175
	v_mfma_f32_16x16x32_bf16 v[240:243], v[224:227], v[16:19], v[240:243]
	v_cvt_pk_bf16_f32 v170, v172, v173
	v_cvt_pk_bf16_f32 v171, v174, v175
	ds_read_b128 v[224:227], v160 offset:28736
	s_waitcnt lgkmcnt(4)
	v_mfma_f32_16x16x32_bf16 v[232:235], v[228:231], v[8:11], v[232:235]
	v_exp_f32_e32 v108, v108
	v_mfma_f32_16x16x32_bf16 v[240:243], v[228:231], v[20:23], v[240:243]
	v_exp_f32_e32 v109, v109
	ds_read_b128 v[228:231], v160 offset:33344
	s_waitcnt lgkmcnt(4)
	v_mfma_f32_16x16x32_bf16 v[236:239], v[212:215], v[0:3], 0
	v_exp_f32_e32 v110, v110
	v_mfma_f32_16x16x32_bf16 v[244:247], v[212:215], v[12:15], 0
	v_exp_f32_e32 v111, v111
	ds_read_b128 v[212:215], v160 offset:37952
	s_waitcnt lgkmcnt(4)
	v_mfma_f32_16x16x32_bf16 v[236:239], v[216:219], v[4:7], v[236:239]
	v_cvt_pk_bf16_f32 v178, v108, v109
	v_cvt_pk_bf16_f32 v179, v110, v111
	v_mfma_f32_16x16x32_bf16 v[244:247], v[216:219], v[16:19], v[244:247]
	v_exp_f32_e32 v232, v232
	ds_read_b128 v[216:219], v160 offset:42560
	s_waitcnt lgkmcnt(4)
	v_mfma_f32_16x16x32_bf16 v[236:239], v[220:223], v[8:11], v[236:239]
	v_exp_f32_e32 v233, v233
	v_mfma_f32_16x16x32_bf16 v[244:247], v[220:223], v[20:23], v[244:247]
	v_exp_f32_e32 v234, v234
	ds_read_b128 v[220:223], v160 offset:47168
	s_waitcnt lgkmcnt(4)
	v_mfma_f32_16x16x32_bf16 v[84:87], v[224:227], v[168:171], v[84:87]
	v_exp_f32_e32 v235, v235
	v_mfma_f32_16x16x32_bf16 v[68:71], v[224:227], v[176:179], v[68:71]
	v_cvt_pk_bf16_f32 v232, v232, v233
	v_cvt_pk_bf16_f32 v233, v234, v235
	ds_read_b128 v[224:227], v165 offset:21504
	s_waitcnt lgkmcnt(4)
	v_mfma_f32_16x16x32_bf16 v[88:91], v[228:231], v[168:171], v[88:91]
	v_exp_f32_e32 v240, v240
	v_mfma_f32_16x16x32_bf16 v[72:75], v[228:231], v[176:179], v[72:75]
	v_exp_f32_e32 v241, v241
	ds_read_b128 v[228:231], v165 offset:21568
	s_waitcnt lgkmcnt(4)
	v_mfma_f32_16x16x32_bf16 v[92:95], v[212:215], v[168:171], v[92:95]
	v_exp_f32_e32 v242, v242
	v_mfma_f32_16x16x32_bf16 v[76:79], v[212:215], v[176:179], v[76:79]
	v_exp_f32_e32 v243, v243
	ds_read_b128 v[212:215], v165 offset:21632
	s_waitcnt lgkmcnt(4)
	v_mfma_f32_16x16x32_bf16 v[96:99], v[216:219], v[168:171], v[96:99]
	v_cvt_pk_bf16_f32 v240, v240, v241
	v_cvt_pk_bf16_f32 v241, v242, v243
	v_mfma_f32_16x16x32_bf16 v[80:83], v[216:219], v[176:179], v[80:83]
	v_exp_f32_e32 v236, v236
	ds_read_b128 v[216:219], v165 offset:25088
	s_waitcnt lgkmcnt(4)
	v_mfma_f32_16x16x32_bf16 v[104:107], v[220:223], v[168:171], v[104:107]
	v_exp_f32_e32 v237, v237
	v_mfma_f32_16x16x32_bf16 v[100:103], v[220:223], v[176:179], v[100:103]
	v_exp_f32_e32 v238, v238
	ds_read_b128 v[220:223], v165 offset:25152
	s_waitcnt lgkmcnt(4)
	v_mfma_f32_16x16x32_bf16 v[168:171], v[224:227], v[0:3], 0
	v_exp_f32_e32 v239, v239
	v_mfma_f32_16x16x32_bf16 v[176:179], v[224:227], v[12:15], 0
	v_cvt_pk_bf16_f32 v234, v236, v237
	v_cvt_pk_bf16_f32 v235, v238, v239
	ds_read_b128 v[224:227], v165 offset:25216
	s_waitcnt lgkmcnt(4)
	v_mfma_f32_16x16x32_bf16 v[168:171], v[228:231], v[4:7], v[168:171]
	v_exp_f32_e32 v244, v244
	v_mfma_f32_16x16x32_bf16 v[176:179], v[228:231], v[16:19], v[176:179]
	v_exp_f32_e32 v245, v245
	ds_read_b128 v[228:231], v160 offset:28800
	s_waitcnt lgkmcnt(4)
	v_mfma_f32_16x16x32_bf16 v[168:171], v[212:215], v[8:11], v[168:171]
	v_exp_f32_e32 v246, v246
	v_mfma_f32_16x16x32_bf16 v[176:179], v[212:215], v[20:23], v[176:179]
	v_exp_f32_e32 v247, v247
	ds_read_b128 v[212:215], v160 offset:33408
	s_waitcnt lgkmcnt(4)
	v_mfma_f32_16x16x32_bf16 v[172:175], v[216:219], v[0:3], 0
	v_cvt_pk_bf16_f32 v242, v244, v245
	v_cvt_pk_bf16_f32 v243, v246, v247
	v_mfma_f32_16x16x32_bf16 v[108:111], v[216:219], v[12:15], 0
	v_exp_f32_e32 v168, v168
	ds_read_b128 v[216:219], v160 offset:38016
	s_waitcnt lgkmcnt(4)
	v_mfma_f32_16x16x32_bf16 v[172:175], v[220:223], v[4:7], v[172:175]
	v_exp_f32_e32 v169, v169
	v_mfma_f32_16x16x32_bf16 v[108:111], v[220:223], v[16:19], v[108:111]
	v_exp_f32_e32 v170, v170
	ds_read_b128 v[220:223], v160 offset:42624
	s_waitcnt lgkmcnt(4)
	v_mfma_f32_16x16x32_bf16 v[172:175], v[224:227], v[8:11], v[172:175]
	v_exp_f32_e32 v171, v171
	v_mfma_f32_16x16x32_bf16 v[108:111], v[224:227], v[20:23], v[108:111]
	v_cvt_pk_bf16_f32 v168, v168, v169
	v_cvt_pk_bf16_f32 v169, v170, v171
	ds_read_b128 v[224:227], v160 offset:47232
	s_waitcnt lgkmcnt(4)
	v_mfma_f32_16x16x32_bf16 v[84:87], v[228:231], v[232:235], v[84:87]
	v_exp_f32_e32 v176, v176
	v_mfma_f32_16x16x32_bf16 v[68:71], v[228:231], v[240:243], v[68:71]
	v_exp_f32_e32 v177, v177
	ds_read_b128 v[228:231], v160 offset:28864
	s_waitcnt lgkmcnt(4)
	v_mfma_f32_16x16x32_bf16 v[88:91], v[212:215], v[232:235], v[88:91]
	v_exp_f32_e32 v178, v178
	v_mfma_f32_16x16x32_bf16 v[72:75], v[212:215], v[240:243], v[72:75]
	v_exp_f32_e32 v179, v179
	ds_read_b128 v[212:215], v160 offset:33472
	s_waitcnt lgkmcnt(4)
	v_mfma_f32_16x16x32_bf16 v[92:95], v[216:219], v[232:235], v[92:95]
	v_cvt_pk_bf16_f32 v176, v176, v177
	v_cvt_pk_bf16_f32 v177, v178, v179
	v_mfma_f32_16x16x32_bf16 v[76:79], v[216:219], v[240:243], v[76:79]
	v_exp_f32_e32 v172, v172
	ds_read_b128 v[216:219], v160 offset:38080
	s_waitcnt lgkmcnt(4)
	v_mfma_f32_16x16x32_bf16 v[96:99], v[220:223], v[232:235], v[96:99]
	v_exp_f32_e32 v173, v173
	v_mfma_f32_16x16x32_bf16 v[80:83], v[220:223], v[240:243], v[80:83]
	v_exp_f32_e32 v174, v174
	ds_read_b128 v[220:223], v160 offset:42688
	s_waitcnt lgkmcnt(4)
	v_mfma_f32_16x16x32_bf16 v[104:107], v[224:227], v[232:235], v[104:107]
	v_exp_f32_e32 v175, v175
	v_mfma_f32_16x16x32_bf16 v[100:103], v[224:227], v[240:243], v[100:103]
	v_cvt_pk_bf16_f32 v170, v172, v173
	v_cvt_pk_bf16_f32 v171, v174, v175
	ds_read_b128 v[224:227], v160 offset:47296
	s_waitcnt lgkmcnt(4)
	v_mfma_f32_16x16x32_bf16 v[84:87], v[228:231], v[168:171], v[84:87]
	v_exp_f32_e32 v108, v108
	s_waitcnt lgkmcnt(3)
	v_mfma_f32_16x16x32_bf16 v[88:91], v[212:215], v[168:171], v[88:91]
	v_exp_f32_e32 v109, v109
	s_waitcnt lgkmcnt(2)
	v_mfma_f32_16x16x32_bf16 v[92:95], v[216:219], v[168:171], v[92:95]
	v_exp_f32_e32 v110, v110
	s_waitcnt lgkmcnt(1)
	v_mfma_f32_16x16x32_bf16 v[96:99], v[220:223], v[168:171], v[96:99]
	v_exp_f32_e32 v111, v111
	s_waitcnt lgkmcnt(0)
	v_mfma_f32_16x16x32_bf16 v[104:107], v[224:227], v[168:171], v[104:107]
	v_cvt_pk_bf16_f32 v178, v108, v109
	v_cvt_pk_bf16_f32 v179, v110, v111
	s_nop 0
	s_nop 0
	v_mfma_f32_16x16x32_bf16 v[68:71], v[228:231], v[176:179], v[68:71]
	v_mfma_f32_16x16x32_bf16 v[72:75], v[212:215], v[176:179], v[72:75]
	v_mfma_f32_16x16x32_bf16 v[76:79], v[216:219], v[176:179], v[76:79]
	v_mfma_f32_16x16x32_bf16 v[80:83], v[220:223], v[176:179], v[80:83]
	v_mfma_f32_16x16x32_bf16 v[100:103], v[224:227], v[176:179], v[100:103]
	s_cmp_eq_u32 s53, 34
	s_cbranch_scc1 .LBB0_1504

.LBB0_1496:
	s_mov_b32 s56, 0x5040100
	s_mov_b32 s57, 0x7060302
	s_waitcnt vmcnt(4)
	ds_write_b128 v161, v[24:27]
	ds_write_b128 v162, v[28:31]
	ds_write_b128 v166, v[32:35]
	ds_write_b128 v167, v[36:39]
	ds_write_b128 v188, v[40:43]
	ds_write_b128 v211, v[48:51]
	s_waitcnt vmcnt(1)
	v_perm_b32 v108, v60, v52, s56
	v_perm_b32 v109, v60, v52, s57
	v_add_u32_e32 v110, 0x7000, v159
	ds_write2_b32 v110, v108, v109 offset1:72
	v_perm_b32 v108, v61, v53, s56
	v_perm_b32 v109, v61, v53, s57
	ds_write2_b32 v110, v108, v109 offset0:144 offset1:216
	v_perm_b32 v108, v62, v54, s56
	v_perm_b32 v109, v62, v54, s57
	v_add_u32_e32 v110, 0x7400, v159
	ds_write2_b32 v110, v108, v109 offset0:32 offset1:104
	v_perm_b32 v108, v63, v55, s56
	v_perm_b32 v109, v63, v55, s57
	ds_write2_b32 v110, v108, v109 offset0:176 offset1:248
	s_waitcnt vmcnt(0)
	v_perm_b32 v108, v64, v56, s56
	v_perm_b32 v109, v64, v56, s57
	v_add_u32_e32 v110, 0x9400, v159
	ds_write2_b32 v110, v108, v109 offset1:72
	v_perm_b32 v108, v65, v57, s56
	v_perm_b32 v109, v65, v57, s57
	ds_write2_b32 v110, v108, v109 offset0:144 offset1:216
	v_perm_b32 v108, v66, v58, s56
	v_perm_b32 v109, v66, v58, s57
	v_add_u32_e32 v110, 0x9800, v159
	ds_write2_b32 v110, v108, v109 offset0:32 offset1:104
	v_perm_b32 v108, v67, v59, s56
	v_perm_b32 v109, v67, v59, s57
	ds_write2_b32 v110, v108, v109 offset0:176 offset1:248
	s_mov_b64 s[20:21], -1
	s_mov_b64 s[16:17], 0
	s_cmp_lt_i32 s53, 33
	s_mov_b64 s[18:19], 0
	s_waitcnt lgkmcnt(0)
	s_barrier
	s_cbranch_scc1 .Lmla_ld
	s_branch .LBB0_1483
